# scan+attention phase: background scan/weight-conversion consume de-serialized (decay and norm-gain loads hoisted out of the dependent chain)
# speedup vs baseline: 1.0170x; 1.0170x over previous
.LBB0_58:
	s_or_b64 exec, exec, s[38:39]
	v_lshlrev_b32_e32 v2, 5, v231
	v_and_b32_e32 v2, 32, v2
	v_ashrrev_i32_e32 v7, 31, v6
	v_add_u32_e32 v174, v3, v2
	v_lshl_add_u64 v[2:3], v[6:7], 2, v[4:5]
	v_add_u32_e32 v102, v174, v178
	v_lshl_add_u64 v[100:101], v[2:3], 0, v[162:163]
	v_mov_b32_e32 v246, 1.0
	v_mov_b32_e32 v247, 1.0
	v_mov_b32_e32 v248, 1.0
	v_mov_b32_e32 v249, 1.0
	v_mov_b32_e32 v250, 1.0
	v_mov_b32_e32 v251, 1.0
	v_mov_b32_e32 v252, 1.0
	v_mov_b32_e32 v253, 1.0
	v_cmp_ne_u64_e32 vcc, 0, v[172:173]
	s_and_saveexec_b64 s[38:39], vcc
	s_cbranch_execz .Lmy_gl_a
	v_lshrrev_b32_e32 v6, 1, v180
	v_add_u32_e32 v6, v6, v174
	v_mov_b32_e32 v7, 0
	v_lshl_add_u64 v[4:5], v[6:7], 2, v[172:173]
	global_load_dwordx4 v[246:249], v[4:5], off
	global_load_dwordx4 v[250:253], v[4:5], off offset:16
.Lmy_gl_a:
	s_or_b64 exec, exec, s[38:39]
	v_mov_b32_e32 v3, 0
	v_mov_b32_e32 v2, 0
	s_and_saveexec_b64 s[38:39], s[88:89]
	s_cbranch_execz .LBB0_60
	v_ashrrev_i32_e32 v2, 31, v102
	v_mul_lo_u32 v6, v99, v102
	v_mul_lo_u32 v2, v98, v2
	v_mad_u64_u32 v[4:5], s[50:51], v98, v102, 0
	v_add3_u32 v5, v5, v2, v6
	v_lshl_add_u64 v[4:5], v[4:5], 2, v[100:101]
	global_load_dword v2, v[4:5], off nt

.LBB0_92:
	s_andn2_saveexec_b64 s[70:71], s[72:73]
	s_cbranch_execz .LBB0_94
	v_ashrrev_i32_e32 v169, 31, v168
	v_and_b32_e32 v241, 15, v229
	v_add_lshl_u32 v241, v241, v168, 5
	global_load_dword v241, v241, s[58:59]
	v_lshlrev_b64 v[2:3], 17, v[168:169]
	v_lshl_add_u64 v[98:99], v[166:167], 0, v[2:3]
	v_add_co_u32_e32 v4, vcc, 0x20000, v98
	global_load_dword v2, v[98:99], off nt
	s_nop 0
	v_addc_co_u32_e32 v5, vcc, 0, v99, vcc
	global_load_dword v3, v[4:5], off nt
	v_add_co_u32_e32 v4, vcc, 0x40000, v98
	s_or_b64 s[88:89], s[88:89], exec
	s_nop 0
	v_addc_co_u32_e32 v5, vcc, 0, v99, vcc
	v_add_co_u32_e32 v6, vcc, 0x60000, v98
	global_load_dword v4, v[4:5], off nt
	s_nop 0
	v_addc_co_u32_e32 v7, vcc, 0, v99, vcc
	global_load_dword v5, v[6:7], off nt
	v_add_co_u32_e32 v6, vcc, 0x80000, v98
	s_or_b64 s[34:35], s[34:35], exec
	s_nop 0
	v_addc_co_u32_e32 v7, vcc, 0, v99, vcc
	v_add_co_u32_e32 v8, vcc, 0xa0000, v98
	global_load_dword v6, v[6:7], off nt
	s_nop 0
	v_addc_co_u32_e32 v9, vcc, 0, v99, vcc
	global_load_dword v7, v[8:9], off nt
	v_add_co_u32_e32 v8, vcc, 0xc0000, v98
	s_nop 1
	v_addc_co_u32_e32 v9, vcc, 0, v99, vcc
	v_add_co_u32_e32 v10, vcc, 0xe0000, v98
	global_load_dword v8, v[8:9], off nt
	s_nop 0
	v_addc_co_u32_e32 v11, vcc, 0, v99, vcc
	global_load_dword v9, v[10:11], off nt
	v_add_co_u32_e32 v10, vcc, 0x100000, v98
	s_nop 1
	v_addc_co_u32_e32 v11, vcc, 0, v99, vcc
	v_add_co_u32_e32 v12, vcc, 0x120000, v98
	global_load_dword v10, v[10:11], off nt
	s_nop 0
	v_addc_co_u32_e32 v13, vcc, 0, v99, vcc
	global_load_dword v11, v[12:13], off nt
	v_add_co_u32_e32 v12, vcc, 0x140000, v98
	s_nop 1
	v_addc_co_u32_e32 v13, vcc, 0, v99, vcc
	v_add_co_u32_e32 v14, vcc, 0x160000, v98
	global_load_dword v12, v[12:13], off nt
	s_nop 0
	v_addc_co_u32_e32 v15, vcc, 0, v99, vcc
	global_load_dword v13, v[14:15], off nt
	v_add_co_u32_e32 v14, vcc, 0x180000, v98
	s_nop 1
	v_addc_co_u32_e32 v15, vcc, 0, v99, vcc
	v_add_co_u32_e32 v16, vcc, 0x1a0000, v98
	global_load_dword v14, v[14:15], off nt
	s_nop 0
	v_addc_co_u32_e32 v17, vcc, 0, v99, vcc
	global_load_dword v15, v[16:17], off nt
	v_add_co_u32_e32 v16, vcc, 0x1c0000, v98
	s_nop 1
	v_addc_co_u32_e32 v17, vcc, 0, v99, vcc
	v_add_co_u32_e32 v98, vcc, 0x1e0000, v98
	global_load_dword v16, v[16:17], off nt
	s_nop 0
	v_addc_co_u32_e32 v99, vcc, 0, v99, vcc
	global_load_dword v17, v[98:99], off nt

.LBB0_99:
	s_waitcnt lgkmcnt(14)
	v_pk_add_f32 v[126:127], v[126:127], v[132:133]
	s_waitcnt lgkmcnt(2)
	v_mov_b32_e32 v139, v136
	v_pk_add_f32 v[214:215], v[128:129], v[140:141]
	v_pk_add_f32 v[114:115], v[114:115], v[142:143]
	v_pk_add_f32 v[142:143], v[110:111], v[154:155]
	v_pk_add_f32 v[110:111], v[100:101], v[206:207]
	v_pk_add_f32 v[100:101], v[102:103], v[138:139]
	v_max3_f32 v102, v126, s10, v127
	v_max3_f32 v102, v102, v214, v215
	v_pk_add_f32 v[116:117], v[116:117], v[156:157]
	v_max3_f32 v102, v102, v114, v115
	v_pk_add_f32 v[128:129], v[124:125], v[134:135]
	v_pk_add_f32 v[134:135], v[118:119], v[146:147]
	v_pk_add_f32 v[118:119], v[106:107], v[150:151]
	v_max3_f32 v102, v102, v116, v117
	v_pk_add_f32 v[108:109], v[108:109], v[160:161]
	v_max3_f32 v102, v102, v118, v119
	v_pk_add_f32 v[140:141], v[112:113], v[148:149]
	v_pk_add_f32 v[112:113], v[98:99], v[158:159]
	v_max3_f32 v102, v102, v108, v109
	v_max3_f32 v102, v102, v112, v113
	v_max3_f32 v102, v102, v110, v111
	ds_bpermute_b32 v103, v239, v102
	v_pk_add_f32 v[132:133], v[120:121], v[144:145]
	v_pk_add_f32 v[130:131], v[122:123], v[130:131]
	s_waitcnt lgkmcnt(1)
	v_pk_add_f32 v[98:99], v[104:105], v[152:153]
	ds_read_b64_tr_b16 v[156:157], v197 offset:50432
	ds_read_b64_tr_b16 v[154:155], v197 offset:41984
	ds_read_b64_tr_b16 v[158:159], v197 offset:42016
	s_waitcnt lgkmcnt(3)
	v_max_f32_e32 v103, v103, v103
	v_max_f32_e32 v102, v102, v103
	ds_bpermute_b32 v103, v238, v102
	s_waitcnt lgkmcnt(0)
	v_max3_f32 v138, v181, v102, v103
	v_sub_f32_e32 v103, v126, v138
	v_exp_f32_e32 v107, v103
	v_sub_f32_e32 v103, v127, v138
	v_exp_f32_e32 v139, v103
	v_sub_f32_e32 v103, v214, v138
	v_exp_f32_e32 v144, v103
	v_sub_f32_e32 v103, v215, v138
	v_exp_f32_e32 v145, v103
	v_sub_f32_e32 v103, v114, v138
	v_exp_f32_e32 v146, v103
	v_sub_f32_e32 v103, v115, v138
	v_exp_f32_e32 v147, v103
	v_sub_f32_e32 v103, v116, v138
	v_sub_f32_e32 v102, v181, v138
	v_exp_f32_e32 v126, v103
	v_sub_f32_e32 v103, v117, v138
	v_exp_f32_e32 v124, v103
	v_sub_f32_e32 v103, v118, v138
	v_exp_f32_e32 v106, v102
	v_max3_f32 v102, v130, s10, v131
	v_exp_f32_e32 v122, v103
	v_sub_f32_e32 v103, v119, v138
	v_max3_f32 v102, v102, v128, v129
	v_exp_f32_e32 v120, v103
	v_sub_f32_e32 v103, v108, v138
	v_max3_f32 v102, v102, v134, v135
	v_exp_f32_e32 v118, v103
	v_sub_f32_e32 v103, v109, v138
	v_max3_f32 v102, v102, v132, v133
	v_exp_f32_e32 v116, v103
	v_sub_f32_e32 v103, v112, v138
	v_max3_f32 v102, v102, v142, v143
	v_exp_f32_e32 v114, v103
	v_sub_f32_e32 v103, v113, v138
	v_max3_f32 v102, v102, v140, v141
	v_exp_f32_e32 v112, v103
	v_sub_f32_e32 v103, v110, v138
	v_max3_f32 v102, v102, v100, v101
	v_exp_f32_e32 v110, v103
	v_sub_f32_e32 v103, v111, v138
	v_max3_f32 v102, v102, v98, v99
	v_exp_f32_e32 v108, v103
	ds_bpermute_b32 v103, v239, v102
	v_pk_mul_f32 v[88:89], v[88:89], v[106:107] op_sel_hi:[1,0]
	v_pk_mul_f32 v[86:87], v[86:87], v[106:107] op_sel_hi:[1,0]
	v_pk_mul_f32 v[92:93], v[92:93], v[106:107] op_sel_hi:[1,0]
	v_pk_mul_f32 v[90:91], v[90:91], v[106:107] op_sel_hi:[1,0]
	s_waitcnt lgkmcnt(0)
	v_max_f32_e32 v103, v103, v103
	v_max_f32_e32 v102, v102, v103
	ds_bpermute_b32 v103, v238, v102
	v_pk_mul_f32 v[84:85], v[84:85], v[106:107] op_sel_hi:[1,0]
	v_pk_mul_f32 v[82:83], v[82:83], v[106:107] op_sel_hi:[1,0]
	v_pk_mul_f32 v[96:97], v[96:97], v[106:107] op_sel_hi:[1,0]
	v_pk_mul_f32 v[94:95], v[94:95], v[106:107] op_sel_hi:[1,0]
	s_waitcnt lgkmcnt(0)
	v_max3_f32 v148, v175, v102, v103
	v_sub_f32_e32 v103, v130, v148
	v_exp_f32_e32 v149, v103
	v_sub_f32_e32 v103, v131, v148
	v_exp_f32_e32 v150, v103
	v_sub_f32_e32 v103, v128, v148
	v_exp_f32_e32 v151, v103
	v_sub_f32_e32 v103, v129, v148
	v_exp_f32_e32 v129, v103
	v_sub_f32_e32 v103, v134, v148
	v_exp_f32_e32 v152, v103
	v_sub_f32_e32 v103, v135, v148
	v_exp_f32_e32 v153, v103
	v_sub_f32_e32 v103, v132, v148
	v_sub_f32_e32 v102, v175, v148
	v_exp_f32_e32 v127, v103
	v_sub_f32_e32 v103, v133, v148
	v_exp_f32_e32 v125, v103
	v_sub_f32_e32 v103, v142, v148
	v_exp_f32_e32 v128, v102
	v_exp_f32_e32 v123, v103
	v_sub_f32_e32 v103, v143, v148
	v_exp_f32_e32 v121, v103
	v_sub_f32_e32 v103, v140, v148
	v_sub_f32_e32 v100, v100, v148
	v_sub_f32_e32 v98, v98, v148
	v_exp_f32_e32 v119, v103
	v_sub_f32_e32 v103, v141, v148
	v_exp_f32_e32 v115, v100
	v_sub_f32_e32 v100, v101, v148
	v_exp_f32_e32 v111, v98
	v_sub_f32_e32 v98, v99, v148
	v_exp_f32_e32 v117, v103
	v_exp_f32_e32 v113, v100
	v_exp_f32_e32 v109, v98
	v_pk_mul_f32 v[24:25], v[24:25], v[128:129] op_sel_hi:[1,0]
	v_pk_mul_f32 v[22:23], v[22:23], v[128:129] op_sel_hi:[1,0]
	v_cvt_pk_bf16_f32 v130, v107, v139
	v_cvt_pk_bf16_f32 v131, v144, v145
	v_cvt_pk_bf16_f32 v132, v146, v147
	v_cvt_pk_bf16_f32 v133, v126, v124
	v_cvt_pk_bf16_f32 v140, v149, v150
	v_cvt_pk_bf16_f32 v141, v151, v129
	v_cvt_pk_bf16_f32 v142, v152, v153
	v_cvt_pk_bf16_f32 v143, v127, v125
	v_mfma_f32_16x16x32_bf16 v[86:89], v[154:157], v[130:133], v[86:89]
	v_mul_f32_e64 v104, v80, v128
	v_mul_f32_e64 v105, v81, v128
	v_pk_mul_f32 v[102:103], v[78:79], v[128:129] op_sel_hi:[1,0]
	v_cvt_pk_bf16_f32 v78, v122, v120
	v_mfma_f32_16x16x32_bf16 v[22:25], v[154:157], v[140:143], v[22:25]
	ds_read_b64_tr_b16 v[154:155], v197 offset:58880
	ds_read_b64_tr_b16 v[156:157], v199 offset:25344
	ds_read_b64_tr_b16 v[244:245], v199 offset:25376
	v_cvt_pk_bf16_f32 v79, v118, v116
	v_cvt_pk_bf16_f32 v80, v114, v112
	v_cvt_pk_bf16_f32 v81, v110, v108
	v_cvt_pk_bf16_f32 v98, v123, v121
	v_cvt_pk_bf16_f32 v99, v119, v117
	v_cvt_pk_bf16_f32 v100, v115, v113
	v_cvt_pk_bf16_f32 v101, v111, v109
	s_waitcnt lgkmcnt(1)
	v_mfma_f32_16x16x32_bf16 v[86:89], v[154:157], v[78:81], v[86:89]
	ds_read_b64_tr_b16 v[160:161], v197 offset:50464
	ds_read_b64_tr_b16 v[242:243], v197 offset:58912
	v_pk_mul_f32 v[44:45], v[44:45], v[128:129] op_sel_hi:[1,0]
	v_mfma_f32_16x16x32_bf16 v[22:25], v[154:157], v[98:101], v[22:25]
	ds_read_b64_tr_b16 v[154:155], v197 offset:42048
	ds_read_b64_tr_b16 v[156:157], v197 offset:50496
	v_pk_mul_f32 v[42:43], v[42:43], v[128:129] op_sel_hi:[1,0]
	v_pk_mul_f32 v[20:21], v[20:21], v[128:129] op_sel_hi:[1,0]
	s_waitcnt lgkmcnt(0)
	v_mfma_f32_16x16x32_bf16 v[90:93], v[154:157], v[130:133], v[90:93]
	v_mul_f32_e64 v18, v18, v128
	v_mul_f32_e64 v19, v19, v128
	v_mfma_f32_16x16x32_bf16 v[42:45], v[154:157], v[140:143], v[42:45]
	ds_read_b64_tr_b16 v[154:155], v197 offset:58944
	ds_read_b64_tr_b16 v[156:157], v199 offset:25408
	s_waitcnt lgkmcnt(0)
	v_mfma_f32_16x16x32_bf16 v[90:93], v[154:157], v[78:81], v[90:93]
	v_mfma_f32_16x16x32_bf16 v[42:45], v[154:157], v[98:101], v[42:45]
	ds_read_b64_tr_b16 v[154:155], v197 offset:42080
	ds_read_b64_tr_b16 v[156:157], v197 offset:50528
	v_mfma_f32_16x16x32_bf16 v[82:85], v[158:161], v[130:133], v[82:85]
	s_waitcnt lgkmcnt(0)
	v_mfma_f32_16x16x32_bf16 v[94:97], v[154:157], v[130:133], v[94:97]
	ds_read_b64_tr_b16 v[130:131], v197 offset:58976
	ds_read_b64_tr_b16 v[132:133], v199 offset:25440
	v_mfma_f32_16x16x32_bf16 v[18:21], v[158:161], v[140:143], v[18:21]
	v_mfma_f32_16x16x32_bf16 v[102:105], v[154:157], v[140:143], v[102:105]
	v_mfma_f32_16x16x32_bf16 v[82:85], v[242:245], v[78:81], v[82:85]
	v_mfma_f32_16x16x32_bf16 v[18:21], v[242:245], v[98:101], v[18:21]
	s_waitcnt lgkmcnt(0)
	v_mfma_f32_16x16x32_bf16 v[94:97], v[130:133], v[78:81], v[94:97]
	v_mfma_f32_16x16x32_bf16 v[78:81], v[130:133], v[98:101], v[102:105]
	s_and_saveexec_b64 s[72:73], s[88:89]
	s_cbranch_execz .LBB0_139
	s_xor_b64 s[38:39], s[34:35], -1
	s_and_saveexec_b64 s[50:51], s[38:39]
	s_xor_b64 s[70:71], exec, s[50:51]
	s_cbranch_execz .LBB0_136
	s_waitcnt vmcnt(0)
	ds_write_b32 v237, v2
	ds_write_b32 v237, v3 offset:264
	ds_write_b32 v237, v4 offset:528
	ds_write_b32 v237, v5 offset:792
	ds_write_b32 v237, v6 offset:1056
	ds_write_b32 v237, v7 offset:1320
	ds_write_b32 v237, v8 offset:1584
	ds_write_b32 v237, v9 offset:1848
	ds_write_b32 v237, v10 offset:2112
	ds_write_b32 v237, v11 offset:2376
	ds_write_b32 v237, v12 offset:2640
	ds_write_b32 v237, v13 offset:2904
	ds_write_b32 v237, v14 offset:3168
	ds_write_b32 v237, v15 offset:3432
	ds_write_b32 v237, v16 offset:3696
	ds_write_b32 v237, v17 offset:3960
	ds_read2_b32 v[104:105], v1 offset1:16
	ds_read2_b32 v[130:131], v1 offset0:33 offset1:49
	ds_read2_b32 v[132:133], v1 offset0:66 offset1:82
	ds_read2_b32 v[134:135], v1 offset0:99 offset1:115
	ds_read2_b32 v[140:141], v1 offset0:132 offset1:148
	ds_read2_b32 v[142:143], v1 offset0:165 offset1:181
	ds_read2_b32 v[154:155], v1 offset0:198 offset1:214
	ds_read2_b32 v[156:157], v1 offset0:231 offset1:247
	v_ashrrev_i32_e32 v175, 31, v174
	v_lshl_add_u64 v[102:103], v[174:175], 1, v[170:171]
	v_mov_b32_e32 v181, v163
	v_lshl_add_u64 v[102:103], v[102:103], 0, v[180:181]
	v_add_u32_e32 v100, v0, v232
	v_mul_lo_u32 v100, v100, v234
	v_mov_b32_e32 v101, 0
	v_lshl_add_u64 v[158:159], v[100:101], 1, v[102:103]
	v_add_u32_e32 v100, v0, v233
	v_mul_lo_u32 v100, v100, v234
	v_lshl_add_u64 v[160:161], v[100:101], 1, v[102:103]
	s_waitcnt lgkmcnt(0)
	v_mul_f32_e32 v104, v246, v104
	v_mul_f32_e32 v130, v247, v130
	v_mul_f32_e32 v132, v248, v132
	v_mul_f32_e32 v134, v249, v134
	v_mul_f32_e32 v140, v250, v140
	v_mul_f32_e32 v142, v251, v142
	v_mul_f32_e32 v154, v252, v154
	v_mul_f32_e32 v156, v253, v156
	v_cvt_pk_bf16_f32 v98, v104, v130
	v_cvt_pk_bf16_f32 v99, v132, v134
	v_cvt_pk_bf16_f32 v100, v140, v142
	v_cvt_pk_bf16_f32 v101, v154, v156
	global_store_dwordx4 v[158:159], v[98:101], off
	v_mul_f32_e32 v105, v246, v105
	v_mul_f32_e32 v131, v247, v131
	v_mul_f32_e32 v133, v248, v133
	v_mul_f32_e32 v135, v249, v135
	v_mul_f32_e32 v141, v250, v141
	v_mul_f32_e32 v143, v251, v143
	v_mul_f32_e32 v155, v252, v155
	v_mul_f32_e32 v157, v253, v157
	v_cvt_pk_bf16_f32 v142, v141, v143
	v_cvt_pk_bf16_f32 v143, v155, v157
	v_cvt_pk_bf16_f32 v140, v105, v131
	v_cvt_pk_bf16_f32 v141, v133, v135
	global_store_dwordx4 v[160:161], v[140:143], off
	v_add_u32_e32 v231, s81, v231
.LBB0_136:
	s_andn2_saveexec_b64 s[88:89], s[70:71]
	s_cbranch_execz .LBB0_138
	s_waitcnt vmcnt(0)
	v_ashrrev_i32_e32 v169, 31, v168
	v_lshlrev_b64 v[98:99], 17, v[168:169]
	v_lshl_add_u64 v[98:99], v[166:167], 0, v[98:99]
	s_mov_b32 s38, 0x20000
	s_mov_b32 s39, 0
	v_readlane_b32 s50, v241, 0
	v_cvt_pk_bf16_f32 v100, v177, v176
	global_store_dword v[98:99], v100, off
	v_lshlrev_b32_e32 v101, 16, v2
	v_and_b32_e32 v102, 0xffff0000, v2
	v_readlane_b32 s51, v241, 1
	v_fma_f32 v177, v177, s50, v101
	v_fma_f32 v176, v176, s50, v102
	v_lshl_add_u64 v[98:99], v[98:99], 0, s[38:39]
	v_cvt_pk_bf16_f32 v100, v177, v176
	global_store_dword v[98:99], v100, off
	v_lshlrev_b32_e32 v101, 16, v3
	v_and_b32_e32 v102, 0xffff0000, v3
	v_readlane_b32 s50, v241, 2
	v_fma_f32 v177, v177, s51, v101
	v_fma_f32 v176, v176, s51, v102
	v_lshl_add_u64 v[98:99], v[98:99], 0, s[38:39]
	v_cvt_pk_bf16_f32 v100, v177, v176
	global_store_dword v[98:99], v100, off
	v_lshlrev_b32_e32 v101, 16, v4
	v_and_b32_e32 v102, 0xffff0000, v4
	v_readlane_b32 s51, v241, 3
	v_fma_f32 v177, v177, s50, v101
	v_fma_f32 v176, v176, s50, v102
	v_lshl_add_u64 v[98:99], v[98:99], 0, s[38:39]
	v_cvt_pk_bf16_f32 v100, v177, v176
	global_store_dword v[98:99], v100, off
	v_lshlrev_b32_e32 v101, 16, v5
	v_and_b32_e32 v102, 0xffff0000, v5
	v_readlane_b32 s50, v241, 4
	v_fma_f32 v177, v177, s51, v101
	v_fma_f32 v176, v176, s51, v102
	v_lshl_add_u64 v[98:99], v[98:99], 0, s[38:39]
	v_cvt_pk_bf16_f32 v100, v177, v176
	global_store_dword v[98:99], v100, off
	v_lshlrev_b32_e32 v101, 16, v6
	v_and_b32_e32 v102, 0xffff0000, v6
	v_readlane_b32 s51, v241, 5
	v_fma_f32 v177, v177, s50, v101
	v_fma_f32 v176, v176, s50, v102
	v_lshl_add_u64 v[98:99], v[98:99], 0, s[38:39]
	v_cvt_pk_bf16_f32 v100, v177, v176
	global_store_dword v[98:99], v100, off
	v_lshlrev_b32_e32 v101, 16, v7
	v_and_b32_e32 v102, 0xffff0000, v7
	v_readlane_b32 s50, v241, 6
	v_fma_f32 v177, v177, s51, v101
	v_fma_f32 v176, v176, s51, v102
	v_lshl_add_u64 v[98:99], v[98:99], 0, s[38:39]
	v_cvt_pk_bf16_f32 v100, v177, v176
	global_store_dword v[98:99], v100, off
	v_lshlrev_b32_e32 v101, 16, v8
	v_and_b32_e32 v102, 0xffff0000, v8
	v_readlane_b32 s51, v241, 7
	v_fma_f32 v177, v177, s50, v101
	v_fma_f32 v176, v176, s50, v102
	v_lshl_add_u64 v[98:99], v[98:99], 0, s[38:39]
	v_cvt_pk_bf16_f32 v100, v177, v176
	global_store_dword v[98:99], v100, off
	v_lshlrev_b32_e32 v101, 16, v9
	v_and_b32_e32 v102, 0xffff0000, v9
	v_readlane_b32 s50, v241, 8
	v_fma_f32 v177, v177, s51, v101
	v_fma_f32 v176, v176, s51, v102
	v_lshl_add_u64 v[98:99], v[98:99], 0, s[38:39]
	v_cvt_pk_bf16_f32 v100, v177, v176
	global_store_dword v[98:99], v100, off
	v_lshlrev_b32_e32 v101, 16, v10
	v_and_b32_e32 v102, 0xffff0000, v10
	v_readlane_b32 s51, v241, 9
	v_fma_f32 v177, v177, s50, v101
	v_fma_f32 v176, v176, s50, v102
	v_lshl_add_u64 v[98:99], v[98:99], 0, s[38:39]
	v_cvt_pk_bf16_f32 v100, v177, v176
	global_store_dword v[98:99], v100, off
	v_lshlrev_b32_e32 v101, 16, v11
	v_and_b32_e32 v102, 0xffff0000, v11
	v_readlane_b32 s50, v241, 10
	v_fma_f32 v177, v177, s51, v101
	v_fma_f32 v176, v176, s51, v102
	v_lshl_add_u64 v[98:99], v[98:99], 0, s[38:39]
	v_cvt_pk_bf16_f32 v100, v177, v176
	global_store_dword v[98:99], v100, off
	v_lshlrev_b32_e32 v101, 16, v12
	v_and_b32_e32 v102, 0xffff0000, v12
	v_readlane_b32 s51, v241, 11
	v_fma_f32 v177, v177, s50, v101
	v_fma_f32 v176, v176, s50, v102
	v_lshl_add_u64 v[98:99], v[98:99], 0, s[38:39]
	v_cvt_pk_bf16_f32 v100, v177, v176
	global_store_dword v[98:99], v100, off
	v_lshlrev_b32_e32 v101, 16, v13
	v_and_b32_e32 v102, 0xffff0000, v13
	v_readlane_b32 s50, v241, 12
	v_fma_f32 v177, v177, s51, v101
	v_fma_f32 v176, v176, s51, v102
	v_lshl_add_u64 v[98:99], v[98:99], 0, s[38:39]
	v_cvt_pk_bf16_f32 v100, v177, v176
	global_store_dword v[98:99], v100, off
	v_lshlrev_b32_e32 v101, 16, v14
	v_and_b32_e32 v102, 0xffff0000, v14
	v_readlane_b32 s51, v241, 13
	v_fma_f32 v177, v177, s50, v101
	v_fma_f32 v176, v176, s50, v102
	v_lshl_add_u64 v[98:99], v[98:99], 0, s[38:39]
	v_cvt_pk_bf16_f32 v100, v177, v176
	global_store_dword v[98:99], v100, off
	v_lshlrev_b32_e32 v101, 16, v15
	v_and_b32_e32 v102, 0xffff0000, v15
	v_readlane_b32 s50, v241, 14
	v_fma_f32 v177, v177, s51, v101
	v_fma_f32 v176, v176, s51, v102
	v_lshl_add_u64 v[98:99], v[98:99], 0, s[38:39]
	v_cvt_pk_bf16_f32 v100, v177, v176
	global_store_dword v[98:99], v100, off
	v_lshlrev_b32_e32 v101, 16, v16
	v_and_b32_e32 v102, 0xffff0000, v16
	v_readlane_b32 s51, v241, 15
	v_fma_f32 v177, v177, s50, v101
	v_fma_f32 v176, v176, s50, v102
	v_lshl_add_u64 v[98:99], v[98:99], 0, s[38:39]
	v_cvt_pk_bf16_f32 v100, v177, v176
	global_store_dword v[98:99], v100, off
	v_lshlrev_b32_e32 v101, 16, v17
	v_and_b32_e32 v102, 0xffff0000, v17
	v_fma_f32 v177, v177, s51, v101
	v_fma_f32 v176, v176, s51, v102
	v_add_u32_e32 v168, 16, v168

.LBB0_170:
	s_or_b64 exec, exec, s[38:39]
	v_lshlrev_b32_e32 v2, 5, v231
	v_and_b32_e32 v2, 32, v2
	v_ashrrev_i32_e32 v7, 31, v6
	v_add_u32_e32 v174, v3, v2
	v_lshl_add_u64 v[2:3], v[6:7], 2, v[4:5]
	v_add_u32_e32 v21, v174, v18
	v_lshl_add_u64 v[24:25], v[2:3], 0, v[162:163]
	v_mov_b32_e32 v246, 1.0
	v_mov_b32_e32 v247, 1.0
	v_mov_b32_e32 v248, 1.0
	v_mov_b32_e32 v249, 1.0
	v_mov_b32_e32 v250, 1.0
	v_mov_b32_e32 v251, 1.0
	v_mov_b32_e32 v252, 1.0
	v_mov_b32_e32 v253, 1.0
	v_cmp_ne_u64_e32 vcc, 0, v[172:173]
	s_and_saveexec_b64 s[38:39], vcc
	s_cbranch_execz .Lmy_gl_b
	v_lshrrev_b32_e32 v6, 1, v20
	v_add_u32_e32 v6, v6, v174
	v_mov_b32_e32 v7, 0
	v_lshl_add_u64 v[4:5], v[6:7], 2, v[172:173]
	global_load_dwordx4 v[246:249], v[4:5], off
	global_load_dwordx4 v[250:253], v[4:5], off offset:16
.Lmy_gl_b:
	s_or_b64 exec, exec, s[38:39]
	v_mov_b32_e32 v3, 0
	v_mov_b32_e32 v2, 0
	s_and_saveexec_b64 s[38:39], s[88:89]
	s_cbranch_execz .LBB0_172
	v_ashrrev_i32_e32 v2, 31, v21
	v_mul_lo_u32 v6, v23, v21
	v_mul_lo_u32 v2, v22, v2
	v_mad_u64_u32 v[4:5], s[16:17], v22, v21, 0
	v_add3_u32 v5, v5, v2, v6
	v_lshl_add_u64 v[4:5], v[4:5], 2, v[24:25]
	global_load_dword v2, v[4:5], off nt

.LBB0_206:
	v_ashrrev_i32_e32 v169, 31, v168
	v_and_b32_e32 v241, 15, v229
	v_add_lshl_u32 v241, v241, v168, 5
	global_load_dword v241, v241, s[58:59]
	v_lshlrev_b64 v[2:3], 17, v[168:169]
	v_lshl_add_u64 v[22:23], v[166:167], 0, v[2:3]
	v_add_co_u32_e32 v4, vcc, 0x20000, v22
	global_load_dword v2, v[22:23], off nt
	s_nop 0
	v_addc_co_u32_e32 v5, vcc, 0, v23, vcc
	global_load_dword v3, v[4:5], off nt
	v_add_co_u32_e32 v4, vcc, 0x40000, v22
	s_or_b64 s[88:89], s[88:89], exec
	s_nop 0
	v_addc_co_u32_e32 v5, vcc, 0, v23, vcc
	v_add_co_u32_e32 v6, vcc, 0x60000, v22
	global_load_dword v4, v[4:5], off nt
	s_nop 0
	v_addc_co_u32_e32 v7, vcc, 0, v23, vcc
	global_load_dword v5, v[6:7], off nt
	v_add_co_u32_e32 v6, vcc, 0x80000, v22
	s_or_b64 s[36:37], s[36:37], exec
	s_nop 0
	v_addc_co_u32_e32 v7, vcc, 0, v23, vcc
	v_add_co_u32_e32 v8, vcc, 0xa0000, v22
	global_load_dword v6, v[6:7], off nt
	s_nop 0
	v_addc_co_u32_e32 v9, vcc, 0, v23, vcc
	global_load_dword v7, v[8:9], off nt
	v_add_co_u32_e32 v8, vcc, 0xc0000, v22
	s_nop 1
	v_addc_co_u32_e32 v9, vcc, 0, v23, vcc
	v_add_co_u32_e32 v10, vcc, 0xe0000, v22
	global_load_dword v8, v[8:9], off nt
	s_nop 0
	v_addc_co_u32_e32 v11, vcc, 0, v23, vcc
	global_load_dword v9, v[10:11], off nt
	v_add_co_u32_e32 v10, vcc, 0x100000, v22
	s_nop 1
	v_addc_co_u32_e32 v11, vcc, 0, v23, vcc
	v_add_co_u32_e32 v12, vcc, 0x120000, v22
	global_load_dword v10, v[10:11], off nt
	s_nop 0
	v_addc_co_u32_e32 v13, vcc, 0, v23, vcc
	global_load_dword v11, v[12:13], off nt
	v_add_co_u32_e32 v12, vcc, 0x140000, v22
	s_nop 1
	v_addc_co_u32_e32 v13, vcc, 0, v23, vcc
	v_add_co_u32_e32 v14, vcc, 0x160000, v22
	global_load_dword v12, v[12:13], off nt
	s_nop 0
	v_addc_co_u32_e32 v15, vcc, 0, v23, vcc
	global_load_dword v13, v[14:15], off nt
	v_add_co_u32_e32 v14, vcc, 0x180000, v22
	s_nop 1
	v_addc_co_u32_e32 v15, vcc, 0, v23, vcc
	v_add_co_u32_e32 v16, vcc, 0x1a0000, v22
	global_load_dword v14, v[14:15], off nt
	s_nop 0
	v_addc_co_u32_e32 v17, vcc, 0, v23, vcc
	global_load_dword v15, v[16:17], off nt
	v_add_co_u32_e32 v16, vcc, 0x1c0000, v22
	s_nop 1
	v_addc_co_u32_e32 v17, vcc, 0, v23, vcc
	v_add_co_u32_e32 v22, vcc, 0x1e0000, v22
	global_load_dword v16, v[16:17], off nt
	s_nop 0
	v_addc_co_u32_e32 v23, vcc, 0, v23, vcc
	global_load_dword v17, v[22:23], off nt
	s_or_b64 exec, exec, s[70:71]
	s_and_saveexec_b64 s[72:73], s[88:89]
	s_cbranch_execz .LBB0_149
.LBB0_207:
	s_xor_b64 s[16:17], s[36:37], -1
	s_and_saveexec_b64 s[22:23], s[16:17]
	s_xor_b64 s[70:71], exec, s[22:23]
	s_cbranch_execz .LBB0_243
	s_waitcnt vmcnt(0)
	ds_write_b32 v29, v2
	ds_write_b32 v29, v3 offset:264
	ds_write_b32 v29, v4 offset:528
	ds_write_b32 v29, v5 offset:792
	ds_write_b32 v29, v6 offset:1056
	ds_write_b32 v29, v7 offset:1320
	ds_write_b32 v29, v8 offset:1584
	ds_write_b32 v29, v9 offset:1848
	ds_write_b32 v29, v10 offset:2112
	ds_write_b32 v29, v11 offset:2376
	ds_write_b32 v29, v12 offset:2640
	ds_write_b32 v29, v13 offset:2904
	ds_write_b32 v29, v14 offset:3168
	ds_write_b32 v29, v15 offset:3432
	ds_write_b32 v29, v16 offset:3696
	ds_write_b32 v29, v17 offset:3960
	ds_read2_b32 v[30:31], v1 offset1:16
	ds_read2_b32 v[32:33], v1 offset0:33 offset1:49
	ds_read2_b32 v[34:35], v1 offset0:66 offset1:82
	ds_read2_b32 v[36:37], v1 offset0:99 offset1:115
	ds_read2_b32 v[38:39], v1 offset0:132 offset1:148
	ds_read2_b32 v[40:41], v1 offset0:165 offset1:181
	ds_read2_b32 v[42:43], v1 offset0:198 offset1:214
	ds_read2_b32 v[44:45], v1 offset0:231 offset1:247
	v_ashrrev_i32_e32 v175, 31, v174
	v_lshl_add_u64 v[50:51], v[174:175], 1, v[170:171]
	v_mov_b32_e32 v21, v163
	v_lshl_add_u64 v[50:51], v[50:51], 0, v[20:21]
	v_add_u32_e32 v52, v0, v232
	v_mul_lo_u32 v52, v52, v234
	v_mov_b32_e32 v53, 0
	v_lshl_add_u64 v[54:55], v[52:53], 1, v[50:51]
	v_add_u32_e32 v52, v0, v233
	v_mul_lo_u32 v52, v52, v234
	v_lshl_add_u64 v[56:57], v[52:53], 1, v[50:51]
	s_waitcnt lgkmcnt(0)
	v_mul_f32_e32 v30, v246, v30
	v_mul_f32_e32 v32, v247, v32
	v_mul_f32_e32 v34, v248, v34
	v_mul_f32_e32 v36, v249, v36
	v_mul_f32_e32 v38, v250, v38
	v_mul_f32_e32 v40, v251, v40
	v_mul_f32_e32 v42, v252, v42
	v_mul_f32_e32 v44, v253, v44
	v_cvt_pk_bf16_f32 v60, v30, v32
	v_cvt_pk_bf16_f32 v61, v34, v36
	v_cvt_pk_bf16_f32 v62, v38, v40
	v_cvt_pk_bf16_f32 v63, v42, v44
	global_store_dwordx4 v[54:55], v[60:63], off
	v_mul_f32_e32 v31, v246, v31
	v_mul_f32_e32 v33, v247, v33
	v_mul_f32_e32 v35, v248, v35
	v_mul_f32_e32 v37, v249, v37
	v_mul_f32_e32 v39, v250, v39
	v_mul_f32_e32 v41, v251, v41
	v_mul_f32_e32 v43, v252, v43
	v_mul_f32_e32 v45, v253, v45
	v_cvt_pk_bf16_f32 v64, v31, v33
	v_cvt_pk_bf16_f32 v65, v35, v37
	v_cvt_pk_bf16_f32 v66, v39, v41
	v_cvt_pk_bf16_f32 v67, v43, v45
	global_store_dwordx4 v[56:57], v[64:67], off
	v_add_u32_e32 v231, s81, v231
.LBB0_243:
	s_andn2_saveexec_b64 s[88:89], s[70:71]
	s_cbranch_execz .LBB0_148
	s_waitcnt vmcnt(0)
	v_ashrrev_i32_e32 v169, 31, v168
	v_lshlrev_b64 v[22:23], 17, v[168:169]
	v_lshl_add_u64 v[22:23], v[166:167], 0, v[22:23]
	s_mov_b32 s16, 0x20000
	s_mov_b32 s17, 0
	v_readlane_b32 s22, v241, 0
	v_cvt_pk_bf16_f32 v24, v177, v176
	global_store_dword v[22:23], v24, off
	v_lshlrev_b32_e32 v25, 16, v2
	v_and_b32_e32 v26, 0xffff0000, v2
	v_readlane_b32 s23, v241, 1
	v_fma_f32 v177, v177, s22, v25
	v_fma_f32 v176, v176, s22, v26
	v_lshl_add_u64 v[22:23], v[22:23], 0, s[16:17]
	v_cvt_pk_bf16_f32 v24, v177, v176
	global_store_dword v[22:23], v24, off
	v_lshlrev_b32_e32 v25, 16, v3
	v_and_b32_e32 v26, 0xffff0000, v3
	v_readlane_b32 s22, v241, 2
	v_fma_f32 v177, v177, s23, v25
	v_fma_f32 v176, v176, s23, v26
	v_lshl_add_u64 v[22:23], v[22:23], 0, s[16:17]
	v_cvt_pk_bf16_f32 v24, v177, v176
	global_store_dword v[22:23], v24, off
	v_lshlrev_b32_e32 v25, 16, v4
	v_and_b32_e32 v26, 0xffff0000, v4
	v_readlane_b32 s23, v241, 3
	v_fma_f32 v177, v177, s22, v25
	v_fma_f32 v176, v176, s22, v26
	v_lshl_add_u64 v[22:23], v[22:23], 0, s[16:17]
	v_cvt_pk_bf16_f32 v24, v177, v176
	global_store_dword v[22:23], v24, off
	v_lshlrev_b32_e32 v25, 16, v5
	v_and_b32_e32 v26, 0xffff0000, v5
	v_readlane_b32 s22, v241, 4
	v_fma_f32 v177, v177, s23, v25
	v_fma_f32 v176, v176, s23, v26
	v_lshl_add_u64 v[22:23], v[22:23], 0, s[16:17]
	v_cvt_pk_bf16_f32 v24, v177, v176
	global_store_dword v[22:23], v24, off
	v_lshlrev_b32_e32 v25, 16, v6
	v_and_b32_e32 v26, 0xffff0000, v6
	v_readlane_b32 s23, v241, 5
	v_fma_f32 v177, v177, s22, v25
	v_fma_f32 v176, v176, s22, v26
	v_lshl_add_u64 v[22:23], v[22:23], 0, s[16:17]
	v_cvt_pk_bf16_f32 v24, v177, v176
	global_store_dword v[22:23], v24, off
	v_lshlrev_b32_e32 v25, 16, v7
	v_and_b32_e32 v26, 0xffff0000, v7
	v_readlane_b32 s22, v241, 6
	v_fma_f32 v177, v177, s23, v25
	v_fma_f32 v176, v176, s23, v26
	v_lshl_add_u64 v[22:23], v[22:23], 0, s[16:17]
	v_cvt_pk_bf16_f32 v24, v177, v176
	global_store_dword v[22:23], v24, off
	v_lshlrev_b32_e32 v25, 16, v8
	v_and_b32_e32 v26, 0xffff0000, v8
	v_readlane_b32 s23, v241, 7
	v_fma_f32 v177, v177, s22, v25
	v_fma_f32 v176, v176, s22, v26
	v_lshl_add_u64 v[22:23], v[22:23], 0, s[16:17]
	v_cvt_pk_bf16_f32 v24, v177, v176
	global_store_dword v[22:23], v24, off
	v_lshlrev_b32_e32 v25, 16, v9
	v_and_b32_e32 v26, 0xffff0000, v9
	v_readlane_b32 s22, v241, 8
	v_fma_f32 v177, v177, s23, v25
	v_fma_f32 v176, v176, s23, v26
	v_lshl_add_u64 v[22:23], v[22:23], 0, s[16:17]
	v_cvt_pk_bf16_f32 v24, v177, v176
	global_store_dword v[22:23], v24, off
	v_lshlrev_b32_e32 v25, 16, v10
	v_and_b32_e32 v26, 0xffff0000, v10
	v_readlane_b32 s23, v241, 9
	v_fma_f32 v177, v177, s22, v25
	v_fma_f32 v176, v176, s22, v26
	v_lshl_add_u64 v[22:23], v[22:23], 0, s[16:17]
	v_cvt_pk_bf16_f32 v24, v177, v176
	global_store_dword v[22:23], v24, off
	v_lshlrev_b32_e32 v25, 16, v11
	v_and_b32_e32 v26, 0xffff0000, v11
	v_readlane_b32 s22, v241, 10
	v_fma_f32 v177, v177, s23, v25
	v_fma_f32 v176, v176, s23, v26
	v_lshl_add_u64 v[22:23], v[22:23], 0, s[16:17]
	v_cvt_pk_bf16_f32 v24, v177, v176
	global_store_dword v[22:23], v24, off
	v_lshlrev_b32_e32 v25, 16, v12
	v_and_b32_e32 v26, 0xffff0000, v12
	v_readlane_b32 s23, v241, 11
	v_fma_f32 v177, v177, s22, v25
	v_fma_f32 v176, v176, s22, v26
	v_lshl_add_u64 v[22:23], v[22:23], 0, s[16:17]
	v_cvt_pk_bf16_f32 v24, v177, v176
	global_store_dword v[22:23], v24, off
	v_lshlrev_b32_e32 v25, 16, v13
	v_and_b32_e32 v26, 0xffff0000, v13
	v_readlane_b32 s22, v241, 12
	v_fma_f32 v177, v177, s23, v25
	v_fma_f32 v176, v176, s23, v26
	v_lshl_add_u64 v[22:23], v[22:23], 0, s[16:17]
	v_cvt_pk_bf16_f32 v24, v177, v176
	global_store_dword v[22:23], v24, off
	v_lshlrev_b32_e32 v25, 16, v14
	v_and_b32_e32 v26, 0xffff0000, v14
	v_readlane_b32 s23, v241, 13
	v_fma_f32 v177, v177, s22, v25
	v_fma_f32 v176, v176, s22, v26
	v_lshl_add_u64 v[22:23], v[22:23], 0, s[16:17]
	v_cvt_pk_bf16_f32 v24, v177, v176
	global_store_dword v[22:23], v24, off
	v_lshlrev_b32_e32 v25, 16, v15
	v_and_b32_e32 v26, 0xffff0000, v15
	v_readlane_b32 s22, v241, 14
	v_fma_f32 v177, v177, s23, v25
	v_fma_f32 v176, v176, s23, v26
	v_lshl_add_u64 v[22:23], v[22:23], 0, s[16:17]
	v_cvt_pk_bf16_f32 v24, v177, v176
	global_store_dword v[22:23], v24, off
	v_lshlrev_b32_e32 v25, 16, v16
	v_and_b32_e32 v26, 0xffff0000, v16
	v_readlane_b32 s23, v241, 15
	v_fma_f32 v177, v177, s22, v25
	v_fma_f32 v176, v176, s22, v26
	v_lshl_add_u64 v[22:23], v[22:23], 0, s[16:17]
	v_cvt_pk_bf16_f32 v24, v177, v176
	global_store_dword v[22:23], v24, off
	v_lshlrev_b32_e32 v25, 16, v17
	v_and_b32_e32 v26, 0xffff0000, v17
	v_fma_f32 v177, v177, s23, v25
	v_fma_f32 v176, v176, s23, v26
	v_add_u32_e32 v168, 16, v168
	s_branch .LBB0_148

	.amdhsa_kernel _Z10fwd_kernel4Args
		.amdhsa_group_segment_fixed_size 0
		.amdhsa_private_segment_fixed_size 0
		.amdhsa_kernarg_size 448
		.amdhsa_user_sgpr_count 2
		.amdhsa_user_sgpr_dispatch_ptr 0
		.amdhsa_user_sgpr_queue_ptr 0
		.amdhsa_user_sgpr_kernarg_segment_ptr 1
		.amdhsa_user_sgpr_dispatch_id 0
		.amdhsa_user_sgpr_kernarg_preload_length 0
		.amdhsa_user_sgpr_kernarg_preload_offset 0
		.amdhsa_user_sgpr_private_segment_size 0
		.amdhsa_uses_dynamic_stack 0
		.amdhsa_enable_private_segment 0
		.amdhsa_system_sgpr_workgroup_id_x 1
		.amdhsa_system_sgpr_workgroup_id_y 0
		.amdhsa_system_sgpr_workgroup_id_z 0
		.amdhsa_system_sgpr_workgroup_info 0
		.amdhsa_system_vgpr_workitem_id 2
		.amdhsa_next_free_vgpr 256
		.amdhsa_next_free_sgpr 102
		.amdhsa_accum_offset 256
		.amdhsa_reserve_vcc 1
		.amdhsa_float_round_mode_32 0
		.amdhsa_float_round_mode_16_64 0
		.amdhsa_float_denorm_mode_32 3
		.amdhsa_float_denorm_mode_16_64 3
		.amdhsa_dx10_clamp 1
		.amdhsa_ieee_mode 1
		.amdhsa_fp16_overflow 0
		.amdhsa_tg_split 0
		.amdhsa_exception_fp_ieee_invalid_op 0
		.amdhsa_exception_fp_denorm_src 0
		.amdhsa_exception_fp_ieee_div_zero 0
		.amdhsa_exception_fp_ieee_overflow 0
		.amdhsa_exception_fp_ieee_underflow 0
		.amdhsa_exception_fp_ieee_inexact 0
		.amdhsa_exception_int_div_zero 0
	.end_amdhsa_kernel

amdhsa.kernels:
  - .agpr_count:     0
    .args:
      - .offset:         0
        .size:           192
        .value_kind:     by_value
      - .offset:         192
        .size:           4
        .value_kind:     hidden_block_count_x
      - .offset:         196
        .size:           4
        .value_kind:     hidden_block_count_y
      - .offset:         200
        .size:           4
        .value_kind:     hidden_block_count_z
      - .offset:         204
        .size:           2
        .value_kind:     hidden_group_size_x
      - .offset:         206
        .size:           2
        .value_kind:     hidden_group_size_y
      - .offset:         208
        .size:           2
        .value_kind:     hidden_group_size_z
      - .offset:         210
        .size:           2
        .value_kind:     hidden_remainder_x
      - .offset:         212
        .size:           2
        .value_kind:     hidden_remainder_y
      - .offset:         214
        .size:           2
        .value_kind:     hidden_remainder_z
      - .offset:         232
        .size:           8
        .value_kind:     hidden_global_offset_x
      - .offset:         240
        .size:           8
        .value_kind:     hidden_global_offset_y
      - .offset:         248
        .size:           8
        .value_kind:     hidden_global_offset_z
      - .offset:         256
        .size:           2
        .value_kind:     hidden_grid_dims
      - .offset:         280
        .size:           8
        .value_kind:     hidden_multigrid_sync_arg
      - .offset:         312
        .size:           4
        .value_kind:     hidden_dynamic_lds_size
    .group_segment_fixed_size: 0
    .kernarg_segment_align: 8
    .kernarg_segment_size: 448
    .language:       OpenCL C
    .language_version:
      - 2
      - 0
    .max_flat_workgroup_size: 512
    .name:           _Z10fwd_kernel4Args
    .private_segment_fixed_size: 0
    .sgpr_count:     108
    .sgpr_spill_count: 76
    .symbol:         _Z10fwd_kernel4Args.kd
    .uniform_work_group_size: 1
    .uses_dynamic_stack: false
    .vgpr_count:     256
    .vgpr_spill_count: 0
    .wavefront_size: 64
